# lever 1 counted vmcnt: attention tile-loop vmcnt(0) split into vmcnt(N) before the K-tile LDS stores and vmcnt(0) before the V^T stores
# baseline (speedup 1.0000x reference)
; template <int D, int DV, int MODE, int NMAP, int KT> ...
;     ...
;         __syncthreads();
;         const int cur = (kt & 1) * BUF_BYTES;
;         if (kt + 1 < nkt) { AT_STORE(((kt + 1) & 1) * BUF_BYTES); if (kt + 2 < nkt) AT_LOAD(kt + 2); }
.LBB0_601:
	s_add_i32 s14, s15, 1
	s_bitcmp1_b32 s14, 0
	s_cselect_b32 s16, 0x11400, 0
	s_add_i32 s16, s16, 0
	v_add3_u32 v130, s16, v161, v162
	s_waitcnt lgkmcnt(0)
	s_barrier
	s_waitcnt vmcnt(4)
	ds_write_b128 v130, v[98:101]
	v_add3_u32 v130, s16, v163, v164
	ds_write_b128 v130, v[102:105]
	v_add3_u32 v130, s16, v165, v166
	s_add_i32 s17, s16, s30
	ds_write_b128 v130, v[106:109]
	v_add3_u32 v130, s16, v167, v168
	s_add_i32 s17, s17, s31
	ds_write_b128 v130, v[110:113]
	v_add_u32_e32 v130, s17, v169
	s_add_i32 s17, s16, s33
	s_add_i32 s17, s17, s34
	s_waitcnt vmcnt(0)
	ds_write_b16 v130, v114 offset:33792
	ds_write_b16_d16_hi v130, v114 offset:33936
	ds_write_b16 v130, v115 offset:34080
	ds_write_b16_d16_hi v130, v115 offset:34224
	ds_write_b16 v130, v116 offset:34368
	ds_write_b16_d16_hi v130, v116 offset:34512
	ds_write_b16 v130, v117 offset:34656
	ds_write_b16_d16_hi v130, v117 offset:34800
	v_add_u32_e32 v130, s17, v169
	s_add_i32 s17, s16, s40
	s_add_i32 s17, s17, s41
	s_add_i32 s16, s16, s42
	ds_write_b16 v130, v118 offset:33792
	ds_write_b16_d16_hi v130, v118 offset:33936
	ds_write_b16 v130, v119 offset:34080
	ds_write_b16_d16_hi v130, v119 offset:34224
	ds_write_b16 v130, v120 offset:34368
	ds_write_b16_d16_hi v130, v120 offset:34512
	ds_write_b16 v130, v121 offset:34656
	ds_write_b16_d16_hi v130, v121 offset:34800
	v_add_u32_e32 v130, s17, v169
	s_add_i32 s16, s16, s43
	ds_write_b16 v130, v122 offset:33792
	ds_write_b16_d16_hi v130, v122 offset:33936
	ds_write_b16 v130, v123 offset:34080
	ds_write_b16_d16_hi v130, v123 offset:34224
	ds_write_b16 v130, v124 offset:34368
	ds_write_b16_d16_hi v130, v124 offset:34512
	ds_write_b16 v130, v125 offset:34656
	ds_write_b16_d16_hi v130, v125 offset:34800
	v_add_u32_e32 v130, s16, v169
	s_cmp_gt_u32 s15, 1
	ds_write_b16 v130, v126 offset:33792
	ds_write_b16_d16_hi v130, v126 offset:33936
	ds_write_b16 v130, v127 offset:34080
	ds_write_b16_d16_hi v130, v127 offset:34224
	ds_write_b16 v130, v128 offset:34368
	ds_write_b16_d16_hi v130, v128 offset:34512
	ds_write_b16 v130, v129 offset:34656
	ds_write_b16_d16_hi v130, v129 offset:34800
	s_cbranch_scc1 .LBB0_603
	v_add_u32_e32 v114, s44, v174
	v_add_u32_e32 v116, s44, v173
	v_add_u32_e32 v122, s44, v172
	v_add_u32_e32 v124, s44, v171
	v_ashrrev_i32_e32 v115, 31, v114
	v_ashrrev_i32_e32 v117, 31, v116
	v_ashrrev_i32_e32 v123, 31, v122
	v_ashrrev_i32_e32 v125, 31, v124
	v_lshlrev_b64 v[114:115], 12, v[114:115]
	v_lshlrev_b64 v[116:117], 12, v[116:117]
	v_lshlrev_b64 v[122:123], 12, v[122:123]
	v_lshlrev_b64 v[124:125], 12, v[124:125]
	v_lshl_add_u64 v[98:99], v[156:157], 0, s[94:95]
	v_lshl_add_u64 v[102:103], v[154:155], 0, s[94:95]
	v_lshl_add_u64 v[106:107], v[152:153], 0, s[94:95]
	v_lshl_add_u64 v[110:111], v[150:151], 0, s[94:95]
	v_lshl_add_u64 v[114:115], s[6:7], 0, v[114:115]
	v_lshl_add_u64 v[118:119], s[8:9], 0, v[116:117]
	v_lshl_add_u64 v[122:123], s[10:11], 0, v[122:123]
	v_lshl_add_u64 v[126:127], s[12:13], 0, v[124:125]
	global_load_dwordx4 v[98:101], v[98:99], off
	s_nop 0
	global_load_dwordx4 v[102:105], v[102:103], off
	s_nop 0
	global_load_dwordx4 v[106:109], v[106:107], off
	s_nop 0
	global_load_dwordx4 v[110:113], v[110:111], off
	s_nop 0
	global_load_dwordx4 v[114:117], v[114:115], off offset:2048
	s_nop 0
	global_load_dwordx4 v[118:121], v[118:119], off offset:2048
	s_nop 0
	global_load_dwordx4 v[122:125], v[122:123], off offset:2048
	s_nop 0
	global_load_dwordx4 v[126:129], v[126:127], off offset:2048

; template <int D, int DV, int MODE, int NMAP, int KT> ...
;     ...
;         __syncthreads();
;         const int cur = (kt & 1) * BUF_BYTES;
;         if (kt + 1 < nkt) { AT_STORE(((kt + 1) & 1) * BUF_BYTES); if (kt + 2 < nkt) AT_LOAD(kt + 2); }
.LBB0_792:
	s_add_i32 s34, s16, 1
	s_cmp_ge_i32 s16, s22
	s_waitcnt lgkmcnt(0)
	s_barrier
	s_cbranch_scc1 .LBB0_795
	s_bitcmp1_b32 s34, 0
	s_cselect_b32 s17, 0xd000, 0
	s_add_i32 s17, s17, 0
	v_add3_u32 v66, s17, v0, v79
	s_add_i32 s40, s17, s23
	s_waitcnt vmcnt(4)
	ds_write_b128 v66, v[42:45]
	v_add3_u32 v66, s17, v84, v85
	s_add_i32 s40, s40, s24
	ds_write_b128 v66, v[46:49]
	v_add_u32_e32 v66, s40, v86
	s_add_i32 s40, s17, s25
	s_add_i32 s40, s40, s26
	s_waitcnt vmcnt(0)
	ds_write_b16 v66, v50 offset:18432
	ds_write_b16_d16_hi v66, v50 offset:18704
	ds_write_b16 v66, v51 offset:18976
	ds_write_b16_d16_hi v66, v51 offset:19248
	ds_write_b16 v66, v52 offset:19520
	ds_write_b16_d16_hi v66, v52 offset:19792
	ds_write_b16 v66, v53 offset:20064
	ds_write_b16_d16_hi v66, v53 offset:20336
	v_add_u32_e32 v66, s40, v86
	s_add_i32 s40, s17, s27
	s_add_i32 s40, s40, s28
	s_add_i32 s17, s17, s29
	ds_write_b16 v66, v54 offset:18432
	ds_write_b16_d16_hi v66, v54 offset:18704
	ds_write_b16 v66, v55 offset:18976
	ds_write_b16_d16_hi v66, v55 offset:19248
	ds_write_b16 v66, v56 offset:19520
	ds_write_b16_d16_hi v66, v56 offset:19792
	ds_write_b16 v66, v57 offset:20064
	ds_write_b16_d16_hi v66, v57 offset:20336
	v_add_u32_e32 v66, s40, v86
	s_add_i32 s17, s17, s30
	ds_write_b16 v66, v58 offset:18432
	ds_write_b16_d16_hi v66, v58 offset:18704
	ds_write_b16 v66, v59 offset:18976
	ds_write_b16_d16_hi v66, v59 offset:19248
	ds_write_b16 v66, v60 offset:19520
	ds_write_b16_d16_hi v66, v60 offset:19792
	ds_write_b16 v66, v61 offset:20064
	ds_write_b16_d16_hi v66, v61 offset:20336
	v_add_u32_e32 v66, s17, v86
	s_add_i32 s17, s16, 2
	s_cmp_gt_i32 s17, s22
	ds_write_b16 v66, v62 offset:18432
	ds_write_b16_d16_hi v66, v62 offset:18704
	ds_write_b16 v66, v63 offset:18976
	ds_write_b16_d16_hi v66, v63 offset:19248
	ds_write_b16 v66, v64 offset:19520
	ds_write_b16_d16_hi v66, v64 offset:19792
	ds_write_b16 v66, v65 offset:20064
	ds_write_b16_d16_hi v66, v65 offset:20336
	s_cbranch_scc1 .LBB0_795
	v_add_u32_e32 v52, s19, v131
	v_mov_b64_e32 v[50:51], s[8:9]
	v_add_u32_e32 v60, s19, v129
	v_mov_b64_e32 v[58:59], s[12:13]
	v_add_u32_e32 v42, s19, v133
	v_add_u32_e32 v44, s19, v132
	v_mad_i64_i32 v[50:51], s[40:41], v52, s57, v[50:51]
	v_add_u32_e32 v54, s19, v130
	v_mov_b64_e32 v[52:53], s[10:11]
	v_mad_i64_i32 v[58:59], s[40:41], v60, s57, v[58:59]
	v_add_u32_e32 v62, s19, v128
	v_mov_b64_e32 v[60:61], s[14:15]
	v_mad_i64_i32 v[42:43], s[40:41], v42, s57, v[80:81]
	v_mad_i64_i32 v[46:47], s[40:41], v44, s57, v[82:83]
	v_mad_i64_i32 v[54:55], s[40:41], v54, s57, v[52:53]
	v_mad_i64_i32 v[62:63], s[40:41], v62, s57, v[60:61]
	global_load_dwordx4 v[42:45], v[42:43], off offset:1536
	s_nop 0
	global_load_dwordx4 v[46:49], v[46:47], off offset:1536
	s_nop 0
	global_load_dwordx4 v[50:53], v[50:51], off offset:2048
	s_nop 0
	global_load_dwordx4 v[54:57], v[54:55], off offset:2048
	s_nop 0
	global_load_dwordx4 v[58:61], v[58:59], off offset:2048
	s_nop 0
	global_load_dwordx4 v[62:65], v[62:63], off offset:2048

; template <int D, int DV, int MODE, int NMAP, int KT> ...
;     ...
;         __syncthreads();
;         const int cur = (kt & 1) * BUF_BYTES;
;         if (kt + 1 < nkt) { AT_STORE(((kt + 1) & 1) * BUF_BYTES); if (kt + 2 < nkt) AT_LOAD(kt + 2); }
.LBB0_1093:
	s_add_i32 s77, s2, 1
	s_cmp_ge_i32 s77, s44
	s_waitcnt lgkmcnt(0)
	s_barrier
	s_cbranch_scc1 .LBB0_1096
	s_bitcmp1_b32 s77, 0
	s_cselect_b32 s3, 0x8c00, 0
	s_add_i32 s3, s3, 0
	v_add3_u32 v98, s3, v135, v144
	s_add_i32 s4, s3, s45
	s_waitcnt vmcnt(2)
	ds_write_b128 v98, v[18:21]
	v_add3_u32 v98, s3, v145, v146
	s_add_i32 s4, s4, s56
	s_add_i32 s3, s3, s61
	ds_write_b128 v98, v[30:33]
	v_add_u32_e32 v98, s4, v147
	s_add_i32 s3, s3, s67
	s_waitcnt vmcnt(0)
	ds_write_b16 v98, v58 offset:17408
	ds_write_b16_d16_hi v98, v58 offset:17552
	ds_write_b16 v98, v59 offset:17696
	ds_write_b16_d16_hi v98, v59 offset:17840
	ds_write_b16 v98, v60 offset:17984
	ds_write_b16_d16_hi v98, v60 offset:18128
	ds_write_b16 v98, v61 offset:18272
	ds_write_b16_d16_hi v98, v61 offset:18416
	v_add_u32_e32 v98, s3, v147
	s_add_i32 s3, s2, 2
	s_cmp_ge_i32 s3, s44
	ds_write_b16 v98, v62 offset:17408
	ds_write_b16_d16_hi v98, v62 offset:17552
	ds_write_b16 v98, v63 offset:17696
	ds_write_b16_d16_hi v98, v63 offset:17840
	ds_write_b16 v98, v64 offset:17984
	ds_write_b16_d16_hi v98, v64 offset:18128
	ds_write_b16 v98, v65 offset:18272
	ds_write_b16_d16_hi v98, v65 offset:18416
	s_cbranch_scc1 .LBB0_1096
	v_add_u32_e32 v60, s76, v155
	v_mov_b64_e32 v[58:59], s[48:49]
	v_add_u32_e32 v18, s76, v154
	v_add_u32_e32 v20, s76, v153
	v_mad_i64_i32 v[58:59], s[4:5], v60, s57, v[58:59]
	v_add_u32_e32 v62, s76, v156
	v_mov_b64_e32 v[60:61], s[50:51]
	v_mad_i64_i32 v[18:19], s[4:5], v18, s57, v[138:139]
	v_mad_i64_i32 v[30:31], s[4:5], v20, s57, v[140:141]
	v_mad_i64_i32 v[62:63], s[4:5], v62, s57, v[60:61]
	global_load_dwordx4 v[18:21], v[18:19], off offset:1024
	s_nop 0
	global_load_dwordx4 v[30:33], v[30:31], off offset:1024
	s_nop 0
	global_load_dwordx4 v[58:61], v[58:59], off offset:2048
	s_nop 0
	global_load_dwordx4 v[62:65], v[62:63], off offset:2048
